# gqa_c: pass-1 row loads and k-gain loads hoisted to loop top, counted vmcnt
# baseline (speedup 1.0000x reference)
; __device__ __forceinline__ float bflo(unsigned u) { return __uint_as_float(u << 16); }
; __device__ __forceinline__ float bfhi(unsigned u) { return __uint_as_float(u & 0xffff0000u); }
; __device__ __forceinline__ void gqa_c(CArgs a, int jl, int gw, int NGW, int lane) {
;     ...
;     for (int m = gw; m < NTOK; m += NGW) {
;         const int t = tok_pos(m); const int pos = half == 0 ? (t >> 6) : (t & 63);
;         const float* cp = COS + pos * 32 + chunk * 8; const float* sp = SIN + pos * 32 + chunk * 8;
;         const f32x4 c0 = *(const f32x4*)cp, c1 = *(const f32x4*)(cp + 4), s0 = *(const f32x4*)sp, s1 = *(const f32x4*)(sp + 4);
; #pragma unroll
;         for (int pass = 0; pass < 2; ++pass) {
;             const int head = pass * 8 + sub; const bool act = head < 10;
;             const int hh = act ? head : 0;
;             bf16_t* p1 = QKV + (size_t)m * 1536 + hh * 128 + half * 64 + chunk * 8; bf16_t* p2 = p1 + 32;
;             const u32x4 a1 = *(const u32x4*)p1, a2 = *(const u32x4*)p2;
;             float x1[8] = {bflo(a1.x), bfhi(a1.x), bflo(a1.y), bfhi(a1.y), bflo(a1.z), bfhi(a1.z), bflo(a1.w), bfhi(a1.w)};
;             float x2[8] = {bflo(a2.x), bfhi(a2.x), bflo(a2.y), bfhi(a2.y), bflo(a2.z), bfhi(a2.z), bflo(a2.w), bfhi(a2.w)};
;             float ss = 0.f;
; #pragma unroll
;             for (int e = 0; e < 8; ++e) ss += x1[e] * x1[e] + x2[e] * x2[e];
;             ss += __shfl_xor(ss, 1); ss += __shfl_xor(ss, 2); ss += __shfl_xor(ss, 4);
;             const float rn = rsqrtf(ss * (1.f / 128.f) + EPS);
;             const float* gn = (hh < 8 ? qn : kn) + half * 64 + chunk * 8;
;             const f32x4 g10 = *(const f32x4*)gn, g11 = *(const f32x4*)(gn + 4), g20 = *(const f32x4*)(gn + 32), g21 = *(const f32x4*)(gn + 36);
;             float y1[8], y2[8];
; #pragma unroll
;             for (int e = 0; e < 8; ++e) { const float c = e < 4 ? c0[e & 3] : c1[e & 3], s = e < 4 ? s0[e & 3] : s1[e & 3];
;                 const float g1 = e < 4 ? g10[e & 3] : g11[e & 3], g2 = e < 4 ? g20[e & 3] : g21[e & 3];
;                 const float u1 = x1[e] * rn * g1, u2 = x2[e] * rn * g2; y1[e] = u1 * c - u2 * s; y2[e] = u2 * c + u1 * s; }
.LBB0_364:
	s_cmpk_lt_i32 s4, 0x4000
	s_movk_i32 s2, 0x7c0
	s_cselect_b32 s2, s2, 0x1fc0
	s_and_b32 s2, s2, s4
	s_lshr_b32 s2, s2, 6
	s_and_b32 s3, s4, 63
	v_mov_b32_e32 v0, s3
	v_mov_b32_e32 v2, s2
	v_cndmask_b32_e32 v0, v0, v2, vcc
	v_lshl_add_u64 v[32:33], v[28:29], 0, v[30:31]
	s_mov_b32 s2, 0x7800000
	v_lshlrev_b32_e32 v0, 7, v0
	v_add_co_u32_e64 v48, s[40:41], s2, v32
	v_lshl_add_u64 v[6:7], v[18:19], 0, v[0:1]
	s_waitcnt vmcnt(4)
	v_lshl_add_u64 v[14:15], v[20:21], 0, v[0:1]
	v_addc_co_u32_e64 v49, s[40:41], 0, v33, s[40:41]
	global_load_dwordx4 v[2:5], v[6:7], off offset:16
	global_load_dwordx4 v[10:13], v[6:7], off
	s_nop 0
	global_load_dwordx4 v[6:9], v[14:15], off offset:16
	s_nop 0
	global_load_dwordx4 v[14:17], v[14:15], off
	s_nop 0
	global_load_dwordx4 v[32:35], v[48:49], off
	global_load_dwordx4 v[36:39], v[48:49], off offset:64
	global_load_dwordx4 v[40:43], v[22:23], off offset:16
	global_load_dwordx4 v[44:47], v[22:23], off
	global_load_dwordx4 v[54:57], v[22:23], off offset:144
	global_load_dwordx4 v[58:61], v[22:23], off offset:128
	s_mov_b64 s[6:7], 0x7800000
	v_lshl_add_u64 v[78:79], v[28:29], 0, v[26:27]
	v_lshl_add_u64 v[78:79], v[78:79], 0, s[6:7]
	global_load_dwordx4 v[80:83], v[78:79], off
	global_load_dwordx4 v[84:87], v[78:79], off offset:64
	global_load_dwordx4 v[88:91], v[24:25], off offset:16
	global_load_dwordx4 v[92:95], v[24:25], off offset:144
	global_load_dwordx4 v[96:99], v[24:25], off
	global_load_dwordx4 v[100:103], v[24:25], off offset:128
	s_waitcnt vmcnt(11)
	v_lshlrev_b32_e32 v70, 16, v33
	v_and_b32_e32 v71, 0xffff0000, v33
	v_lshlrev_b32_e32 v76, 16, v32
	v_and_b32_e32 v77, 0xffff0000, v32
	s_waitcnt vmcnt(10)
	v_lshlrev_b32_e32 v32, 16, v36
	v_and_b32_e32 v33, 0xffff0000, v36
	v_lshlrev_b32_e32 v72, 16, v37
	v_and_b32_e32 v73, 0xffff0000, v37
	v_pk_mul_f32 v[36:37], v[32:33], v[32:33]
	v_pk_mul_f32 v[74:75], v[72:73], v[72:73]
	v_pk_fma_f32 v[36:37], v[76:77], v[76:77], v[36:37]
	v_lshlrev_b32_e32 v62, 16, v35
	v_and_b32_e32 v63, 0xffff0000, v35
	v_lshlrev_b32_e32 v68, 16, v34
	v_and_b32_e32 v69, 0xffff0000, v34
	v_lshlrev_b32_e32 v34, 16, v38
	v_and_b32_e32 v35, 0xffff0000, v38
	v_pk_fma_f32 v[74:75], v[70:71], v[70:71], v[74:75]
	v_add_f32_e32 v0, v36, v37
	v_lshlrev_b32_e32 v64, 16, v39
	v_and_b32_e32 v65, 0xffff0000, v39
	v_pk_mul_f32 v[38:39], v[34:35], v[34:35]
	v_add_f32_e32 v0, v74, v0
	v_pk_fma_f32 v[38:39], v[68:69], v[68:69], v[38:39]
	v_add_f32_e32 v0, v75, v0
	v_pk_mul_f32 v[66:67], v[64:65], v[64:65]
	v_add_f32_e32 v0, v38, v0
	v_pk_fma_f32 v[66:67], v[62:63], v[62:63], v[66:67]
	v_add_f32_e32 v0, v39, v0
	v_add_f32_e32 v0, v66, v0
	v_add_f32_e32 v0, v67, v0
	ds_bpermute_b32 v36, v50, v0
	s_waitcnt lgkmcnt(0)
	v_add_f32_e32 v0, v0, v36
	ds_bpermute_b32 v36, v51, v0
	s_waitcnt lgkmcnt(0)
	v_add_f32_e32 v0, v0, v36
	ds_bpermute_b32 v36, v52, v0
	s_waitcnt lgkmcnt(0)
	v_add_f32_e32 v0, v0, v36
	v_fmamk_f32 v0, v0, 0x3c000000, v201
	v_cmp_gt_f32_e64 s[40:41], s55, v0
	v_mul_f32_e32 v36, 0x4b800000, v0
	s_nop 0
	v_cndmask_b32_e64 v0, v0, v36, s[40:41]
	v_rsq_f32_e32 v0, v0
	s_nop 0
	v_mul_f32_e32 v36, 0x45800000, v0
	v_cndmask_b32_e64 v0, v0, v36, s[40:41]
	v_pk_mul_f32 v[32:33], v[0:1], v[32:33] op_sel_hi:[0,1]
	v_pk_mul_f32 v[36:37], v[0:1], v[76:77] op_sel_hi:[0,1]
	s_waitcnt vmcnt(6)
	v_pk_mul_f32 v[32:33], v[58:59], v[32:33]
	v_pk_mul_f32 v[36:37], v[44:45], v[36:37]
	v_pk_mul_f32 v[38:39], v[10:11], v[32:33]
	v_pk_mul_f32 v[32:33], v[14:15], v[32:33]
	v_pk_mul_f32 v[44:45], v[0:1], v[72:73] op_sel_hi:[0,1]
	v_pk_fma_f32 v[38:39], v[14:15], v[36:37], v[38:39]
	v_pk_fma_f32 v[32:33], v[10:11], v[36:37], v[32:33] neg_lo:[0,0,1] neg_hi:[0,0,1]
	v_pk_mul_f32 v[36:37], v[0:1], v[70:71] op_sel_hi:[0,1]
	v_pk_mul_f32 v[44:45], v[60:61], v[44:45]
	v_pk_mul_f32 v[36:37], v[46:47], v[36:37]
	v_pk_mul_f32 v[46:47], v[12:13], v[44:45]
	v_pk_mul_f32 v[44:45], v[16:17], v[44:45]
	v_pk_mul_f32 v[34:35], v[0:1], v[34:35] op_sel_hi:[0,1]
	v_pk_fma_f32 v[46:47], v[16:17], v[36:37], v[46:47]
	v_pk_fma_f32 v[36:37], v[12:13], v[36:37], v[44:45] neg_lo:[0,0,1] neg_hi:[0,0,1]
	v_pk_mul_f32 v[44:45], v[0:1], v[68:69] op_sel_hi:[0,1]
	v_pk_mul_f32 v[34:35], v[54:55], v[34:35]
	v_pk_mul_f32 v[40:41], v[40:41], v[44:45]
	v_pk_mul_f32 v[44:45], v[2:3], v[34:35]
	v_pk_mul_f32 v[34:35], v[6:7], v[34:35]
	v_pk_fma_f32 v[44:45], v[6:7], v[40:41], v[44:45]
	v_pk_fma_f32 v[34:35], v[2:3], v[40:41], v[34:35] neg_lo:[0,0,1] neg_hi:[0,0,1]
	v_pk_mul_f32 v[40:41], v[0:1], v[62:63] op_sel_hi:[0,1]
	v_pk_mul_f32 v[40:41], v[42:43], v[40:41]
	v_pk_mul_f32 v[42:43], v[0:1], v[64:65] op_sel_hi:[0,1]
	v_pk_mul_f32 v[42:43], v[56:57], v[42:43]
	v_cvt_pk_bf16_f32 v32, v32, v33
	v_pk_mul_f32 v[54:55], v[8:9], v[42:43]
	v_pk_mul_f32 v[42:43], v[4:5], v[42:43]
	v_pk_fma_f32 v[54:55], v[4:5], v[40:41], v[54:55] neg_lo:[0,0,1] neg_hi:[0,0,1]
	v_pk_fma_f32 v[40:41], v[8:9], v[40:41], v[42:43]
	v_cvt_pk_bf16_f32 v33, v36, v37
	v_cvt_pk_bf16_f32 v34, v34, v35
	v_cvt_pk_bf16_f32 v35, v54, v55
	v_cvt_pk_bf16_f32 v36, v38, v39
	v_cvt_pk_bf16_f32 v37, v46, v47
	v_cvt_pk_bf16_f32 v38, v44, v45
	v_cvt_pk_bf16_f32 v39, v40, v41
	global_store_dwordx4 v[48:49], v[32:35], off
	global_store_dwordx4 v[48:49], v[36:39], off offset:64
	s_nop 0
	v_lshl_add_u64 v[32:33], v[28:29], 0, v[26:27]
	s_waitcnt vmcnt(7)
	v_lshlrev_b32_e32 v34, 16, v80
	s_waitcnt vmcnt(6)
	v_lshlrev_b32_e32 v36, 16, v84
	v_and_b32_e32 v37, 0xffff0000, v84
	v_and_b32_e32 v35, 0xffff0000, v80
	v_pk_mul_f32 v[38:39], v[36:37], v[36:37]
	v_lshlrev_b32_e32 v40, 16, v81
	v_pk_fma_f32 v[58:59], v[34:35], v[34:35], v[38:39]
	v_lshlrev_b32_e32 v38, 16, v85
	v_and_b32_e32 v39, 0xffff0000, v85
	v_and_b32_e32 v41, 0xffff0000, v81
	v_pk_mul_f32 v[44:45], v[38:39], v[38:39]
	v_lshlrev_b32_e32 v48, 16, v86
	v_pk_fma_f32 v[54:55], v[40:41], v[40:41], v[44:45]
	v_and_b32_e32 v49, 0xffff0000, v86
	v_add_f32_e32 v0, v58, v59
	v_lshlrev_b32_e32 v46, 16, v82
	v_and_b32_e32 v47, 0xffff0000, v82
	v_pk_mul_f32 v[44:45], v[48:49], v[48:49]
	v_add_f32_e32 v0, v54, v0
	v_pk_fma_f32 v[60:61], v[46:47], v[46:47], v[44:45]
	v_lshlrev_b32_e32 v44, 16, v83
	v_and_b32_e32 v45, 0xffff0000, v83
	v_lshlrev_b32_e32 v42, 16, v87
	v_and_b32_e32 v43, 0xffff0000, v87
	v_add_f32_e32 v0, v55, v0
	v_pk_mul_f32 v[56:57], v[42:43], v[42:43]
	v_add_f32_e32 v0, v60, v0
	v_pk_fma_f32 v[56:57], v[44:45], v[44:45], v[56:57]
	v_add_f32_e32 v0, v61, v0
	v_add_f32_e32 v0, v56, v0
	v_add_f32_e32 v0, v57, v0
	ds_bpermute_b32 v53, v50, v0
	s_waitcnt lgkmcnt(0)
	v_add_f32_e32 v0, v0, v53
	ds_bpermute_b32 v53, v51, v0
	s_waitcnt lgkmcnt(0)
	v_add_f32_e32 v0, v0, v53
	ds_bpermute_b32 v53, v52, v0
	s_and_saveexec_b64 s[2:3], s[38:39]
	s_cbranch_execz .LBB0_363
; __device__ __forceinline__ unsigned pk2(float lo, float hi) { f32x2_t v = {lo, hi}; bf16x2_t b = __builtin_convertvector(v, bf16x2_t); return __builtin_bit_cast(unsigned, b); }
; __device__ __forceinline__ void gqa_c(CArgs a, int jl, int gw, int NGW, int lane) {
;     ...
;             ss += __shfl_xor(ss, 1); ss += __shfl_xor(ss, 2); ss += __shfl_xor(ss, 4);
;             const float rn = rsqrtf(ss * (1.f / 128.f) + EPS);
;             const float* gn = (hh < 8 ? qn : kn) + half * 64 + chunk * 8;
;             const f32x4 g10 = *(const f32x4*)gn, g11 = *(const f32x4*)(gn + 4), g20 = *(const f32x4*)(gn + 32), g21 = *(const f32x4*)(gn + 36);
;             float y1[8], y2[8];
; #pragma unroll
;             for (int e = 0; e < 8; ++e) { const float c = e < 4 ? c0[e & 3] : c1[e & 3], s = e < 4 ? s0[e & 3] : s1[e & 3];
;                 const float g1 = e < 4 ? g10[e & 3] : g11[e & 3], g2 = e < 4 ? g20[e & 3] : g21[e & 3];
;                 const float u1 = x1[e] * rn * g1, u2 = x2[e] * rn * g2; y1[e] = u1 * c - u2 * s; y2[e] = u2 * c + u1 * s; }
;             if (act) {
;                 u32x4 w1 = {pk2(y1[0], y1[1]), pk2(y1[2], y1[3]), pk2(y1[4], y1[5]), pk2(y1[6], y1[7])};
;                 u32x4 w2 = {pk2(y2[0], y2[1]), pk2(y2[2], y2[3]), pk2(y2[4], y2[5]), pk2(y2[6], y2[7])};
;                 *(u32x4*)p1 = w1; *(u32x4*)p2 = w2;
;             }
	s_waitcnt lgkmcnt(0)
	v_add_f32_e32 v0, v0, v53
	v_fmamk_f32 v0, v0, 0x3c000000, v201
	v_mul_f32_e32 v53, 0x4b800000, v0
	v_cmp_gt_f32_e64 s[40:41], s55, v0
	s_mov_b64 s[6:7], 0x7800000
	v_lshl_add_u64 v[70:71], v[32:33], 0, s[6:7]
	v_cndmask_b32_e64 v0, v0, v53, s[40:41]
	v_rsq_f32_e32 v0, v0
	s_mov_b64 s[6:7], 0x7800040
	v_lshl_add_u64 v[32:33], v[32:33], 0, s[6:7]
	v_mul_f32_e32 v53, 0x45800000, v0
	v_cndmask_b32_e64 v0, v0, v53, s[40:41]
	v_pk_mul_f32 v[48:49], v[0:1], v[48:49] op_sel_hi:[0,1]
	v_pk_mul_f32 v[38:39], v[0:1], v[38:39] op_sel_hi:[0,1]
	v_pk_mul_f32 v[36:37], v[0:1], v[36:37] op_sel_hi:[0,1]
	v_pk_mul_f32 v[42:43], v[0:1], v[42:43] op_sel_hi:[0,1]
	v_pk_mul_f32 v[46:47], v[0:1], v[46:47] op_sel_hi:[0,1]
	v_pk_mul_f32 v[40:41], v[0:1], v[40:41] op_sel_hi:[0,1]
	v_pk_mul_f32 v[34:35], v[0:1], v[34:35] op_sel_hi:[0,1]
	v_pk_mul_f32 v[44:45], v[0:1], v[44:45] op_sel_hi:[0,1]
	s_waitcnt vmcnt(5)
	v_pk_mul_f32 v[46:47], v[46:47], v[88:89]
	s_waitcnt vmcnt(4)
	v_pk_mul_f32 v[48:49], v[48:49], v[92:93]
	v_pk_mul_f32 v[42:43], v[42:43], v[94:95]
	s_waitcnt vmcnt(2)
	v_pk_mul_f32 v[38:39], v[38:39], v[102:103]
	v_pk_mul_f32 v[36:37], v[36:37], v[100:101]
	v_pk_mul_f32 v[40:41], v[40:41], v[98:99]
	v_pk_mul_f32 v[34:35], v[34:35], v[96:97]
	v_pk_mul_f32 v[44:45], v[44:45], v[90:91]
	v_pk_mul_f32 v[54:55], v[2:3], v[48:49]
	v_pk_mul_f32 v[48:49], v[6:7], v[48:49]
	v_pk_mul_f32 v[56:57], v[12:13], v[38:39]
	v_pk_mul_f32 v[38:39], v[16:17], v[38:39]
	v_pk_mul_f32 v[58:59], v[10:11], v[36:37]
	v_pk_mul_f32 v[36:37], v[14:15], v[36:37]
	v_pk_mul_f32 v[60:61], v[8:9], v[42:43]
	v_pk_mul_f32 v[42:43], v[4:5], v[42:43]
	v_pk_fma_f32 v[54:55], v[6:7], v[46:47], v[54:55]
	v_pk_fma_f32 v[6:7], v[2:3], v[46:47], v[48:49] neg_lo:[0,0,1] neg_hi:[0,0,1]
	v_pk_fma_f32 v[12:13], v[12:13], v[40:41], v[38:39] neg_lo:[0,0,1] neg_hi:[0,0,1]
	v_pk_fma_f32 v[2:3], v[10:11], v[34:35], v[36:37] neg_lo:[0,0,1] neg_hi:[0,0,1]
	v_pk_fma_f32 v[10:11], v[4:5], v[44:45], v[60:61] neg_lo:[0,0,1] neg_hi:[0,0,1]
	v_pk_fma_f32 v[16:17], v[16:17], v[40:41], v[56:57]
	v_pk_fma_f32 v[14:15], v[14:15], v[34:35], v[58:59]
	v_pk_fma_f32 v[34:35], v[8:9], v[44:45], v[42:43]
	v_cvt_pk_bf16_f32 v2, v2, v3
	v_cvt_pk_bf16_f32 v3, v12, v13
	v_cvt_pk_bf16_f32 v4, v6, v7
	v_cvt_pk_bf16_f32 v5, v10, v11
	v_cvt_pk_bf16_f32 v6, v14, v15
	v_cvt_pk_bf16_f32 v7, v16, v17
	v_cvt_pk_bf16_f32 v8, v54, v55
	v_cvt_pk_bf16_f32 v9, v34, v35
	global_store_dwordx4 v[70:71], v[2:5], off
	global_store_dwordx4 v[32:33], v[6:9], off
	s_branch .LBB0_363
